# gMLP staging: v tile fetched as full 256-byte rows (4 rows per wave instruction) with an XOR-swizzled transposed LDS image
# speedup vs baseline: 1.0043x; 1.0043x over previous
.LBB0_784:
	s_cmpk_gt_i32 s97, 0x3ff
	s_cbranch_scc1 .LBB0_800
	s_waitcnt lgkmcnt(0)
	v_and_b32_e32 v1, 15, v0
	v_bfe_u32 v2, v0, 4, 2
	v_readfirstlane_b32 s4, v0
	s_and_b32 s5, s97, 7
	v_mov_b32_e32 v11, 0x358637bd
	v_and_b32_e32 v110, 15, v0
	v_lshrrev_b32_e32 v111, 4, v0
	s_lshr_b32 s4, s4, 6
	v_lshl_add_u32 v3, s4, 4, v1
	s_lshr_b32 s28, s4, 1
	s_lshl_b32 s26, s5, 8
	s_add_u32 s20, s92, 0xe400000
	s_addc_u32 s21, s93, 0
	s_add_u32 s20, s20, s26
	s_addc_u32 s21, s21, 0
	s_add_u32 s22, s92, 0x6400800
	s_addc_u32 s23, s93, 0
	s_add_u32 s22, s22, s26
	s_addc_u32 s23, s23, 0
	s_add_u32 s24, s92, 0x1cc10000
	s_addc_u32 s25, s93, 0
	v_mul_u32_u24_e32 v4, 0x2a00, v111
	v_lshl_add_u32 v4, v110, 4, v4
	v_add_u32_e32 v236, 0x54000, v4
	v_add_u32_e32 v237, 0x54000, v236
	v_add_u32_e32 v238, 0x54000, v237
	v_lshlrev_b32_e32 v5, 2, v111
	v_lshrrev_b32_e32 v228, 7, v0
	v_and_b32_e32 v229, 7, v111
	v_mul_u32_u24_e32 v227, 0x880, v110
	v_lshl_add_u32 v227, v229, 1, v227
	v_add_u32_e32 v226, 0, v228
	v_xor_b32_e32 v226, v226, v110
	v_lshl_add_u32 v6, v226, 4, v227
	v_add_u32_e32 v226, 4, v228
	v_xor_b32_e32 v226, v226, v110
	v_lshl_add_u32 v239, v226, 4, v227
	v_add_u32_e32 v226, 8, v228
	v_xor_b32_e32 v226, v226, v110
	v_lshl_add_u32 v240, v226, 4, v227
	v_add_u32_e32 v226, 12, v228
	v_xor_b32_e32 v226, v226, v110
	v_lshl_add_u32 v241, v226, 4, v227
	v_mul_u32_u24_e32 v7, 0x2a00, v3
	v_lshl_add_u32 v7, v2, 4, v7
	v_lshlrev_b32_e32 v8, 12, v3
	v_lshl_add_u32 v8, v2, 4, v8
	v_lshrrev_b32_e32 v9, 2, v1
	v_and_b32_e32 v229, 3, v1
	v_xor_b32_e32 v226, v2, v9
	v_lshl_add_u32 v9, v9, 3, v229
	v_mul_u32_u24_e32 v9, 0x110, v9
	v_lshl_add_u32 v9, v226, 4, v9
	s_lshl_b32 s26, s5, 16
	s_add_u32 s6, s84, s26
	s_addc_u32 s7, s85, 0
	v_lshlrev_b32_e32 v224, 9, v3
	v_lshl_add_u32 v224, v2, 5, v224
	global_load_dwordx4 v[60:63], v224, s[6:7] offset:0
	global_load_dwordx4 v[64:67], v224, s[6:7] offset:16
	global_load_dwordx4 v[68:71], v224, s[6:7] offset:128
	global_load_dwordx4 v[72:75], v224, s[6:7] offset:144
	global_load_dwordx4 v[76:79], v224, s[6:7] offset:256
	global_load_dwordx4 v[80:83], v224, s[6:7] offset:272
	global_load_dwordx4 v[84:87], v224, s[6:7] offset:384
	global_load_dwordx4 v[88:91], v224, s[6:7] offset:400
	s_lshl_b32 s26, s5, 9
	s_add_u32 s30, s82, s26
	s_addc_u32 s31, s83, 0
	v_lshlrev_b32_e32 v225, 5, v110
	global_load_dwordx4 v[28:31], v225, s[30:31]
	global_load_dwordx4 v[32:35], v225, s[30:31] offset:16
	s_add_u32 s32, s86, s26
	s_addc_u32 s33, s87, 0
	v_lshlrev_b32_e32 v226, 2, v3
	global_load_dword v10, v226, s[32:33]
	s_mov_b32 s8, s97
	s_lshr_b32 s9, s8, 3
	s_mul_i32 s27, s9, 0x150000
	s_add_u32 s14, s20, s27
	s_addc_u32 s15, s21, 0
	s_add_u32 s14, s14, 0x1200
	s_addc_u32 s15, s15, 0
	s_add_u32 s10, s14, 0x800
	s_addc_u32 s11, s15, 0
	s_add_u32 s16, s14, 0x1000
	s_addc_u32 s17, s15, 0
	s_lshl_b32 s27, s9, 9
	s_add_u32 s12, s24, s27
	s_addc_u32 s13, s25, 0
	global_load_dwordx4 v[92:95], v4, s[10:11]
	global_load_dwordx4 v[96:99], v236, s[10:11]
	global_load_dwordx4 v[100:103], v237, s[10:11]
	global_load_dwordx4 v[104:107], v238, s[10:11]
	global_load_dword v36, v5, s[12:13]
	global_load_dword v37, v5, s[12:13] offset:128
	global_load_dword v38, v5, s[12:13] offset:256
	global_load_dword v39, v5, s[12:13] offset:384
	global_load_dwordx4 v[128:131], v7, s[14:15]
	global_load_dwordx4 v[132:135], v7, s[14:15] offset:64
	global_load_dwordx4 v[136:139], v7, s[14:15] offset:128
	global_load_dwordx4 v[140:143], v7, s[14:15] offset:192
	global_load_dwordx4 v[144:147], v7, s[16:17]
	global_load_dwordx4 v[148:151], v7, s[16:17] offset:64
	global_load_dwordx4 v[152:155], v7, s[16:17] offset:128
	global_load_dwordx4 v[156:159], v7, s[16:17] offset:192
	s_lshr_b32 s9, s8, 3
	s_lshl_b32 s27, s9, 19
	s_add_u32 s18, s22, s27
	s_addc_u32 s19, s23, 0
	s_waitcnt vmcnt(0)
	v_lshlrev_b32_e32 v227, 3, v2
	v_add_u32_e32 v228, 0, v227
	v_cmp_gt_u32_e32 vcc, v228, v3
	s_nop 1
	v_cndmask_b32_e64 v60, v60, 0, vcc
	v_add_u32_e32 v228, 1, v227
	v_cmp_gt_u32_e32 vcc, v228, v3
	s_nop 1
	v_cndmask_b32_e64 v61, v61, 0, vcc
	v_add_u32_e32 v228, 2, v227
	v_cmp_gt_u32_e32 vcc, v228, v3
	s_nop 1
	v_cndmask_b32_e64 v62, v62, 0, vcc
	v_add_u32_e32 v228, 3, v227
	v_cmp_gt_u32_e32 vcc, v228, v3
	s_nop 1
	v_cndmask_b32_e64 v63, v63, 0, vcc
	v_add_u32_e32 v228, 4, v227
	v_cmp_gt_u32_e32 vcc, v228, v3
	s_nop 1
	v_cndmask_b32_e64 v64, v64, 0, vcc
	v_add_u32_e32 v228, 5, v227
	v_cmp_gt_u32_e32 vcc, v228, v3
	s_nop 1
	v_cndmask_b32_e64 v65, v65, 0, vcc
	v_add_u32_e32 v228, 6, v227
	v_cmp_gt_u32_e32 vcc, v228, v3
	s_nop 1
	v_cndmask_b32_e64 v66, v66, 0, vcc
	v_add_u32_e32 v228, 7, v227
	v_cmp_gt_u32_e32 vcc, v228, v3
	s_nop 1
	v_cndmask_b32_e64 v67, v67, 0, vcc
	v_add_u32_e32 v228, 32, v227
	v_cmp_gt_u32_e32 vcc, v228, v3
	s_nop 1
	v_cndmask_b32_e64 v68, v68, 0, vcc
	v_add_u32_e32 v228, 33, v227
	v_cmp_gt_u32_e32 vcc, v228, v3
	s_nop 1
	v_cndmask_b32_e64 v69, v69, 0, vcc
	v_add_u32_e32 v228, 34, v227
	v_cmp_gt_u32_e32 vcc, v228, v3
	s_nop 1
	v_cndmask_b32_e64 v70, v70, 0, vcc
	v_add_u32_e32 v228, 35, v227
	v_cmp_gt_u32_e32 vcc, v228, v3
	s_nop 1
	v_cndmask_b32_e64 v71, v71, 0, vcc
	v_add_u32_e32 v228, 36, v227
	v_cmp_gt_u32_e32 vcc, v228, v3
	s_nop 1
	v_cndmask_b32_e64 v72, v72, 0, vcc
	v_add_u32_e32 v228, 37, v227
	v_cmp_gt_u32_e32 vcc, v228, v3
	s_nop 1
	v_cndmask_b32_e64 v73, v73, 0, vcc
	v_add_u32_e32 v228, 38, v227
	v_cmp_gt_u32_e32 vcc, v228, v3
	s_nop 1
	v_cndmask_b32_e64 v74, v74, 0, vcc
	v_add_u32_e32 v228, 39, v227
	v_cmp_gt_u32_e32 vcc, v228, v3
	s_nop 1
	v_cndmask_b32_e64 v75, v75, 0, vcc
	v_add_u32_e32 v228, 64, v227
	v_cmp_gt_u32_e32 vcc, v228, v3
	s_nop 1
	v_cndmask_b32_e64 v76, v76, 0, vcc
	v_add_u32_e32 v228, 65, v227
	v_cmp_gt_u32_e32 vcc, v228, v3
	s_nop 1
	v_cndmask_b32_e64 v77, v77, 0, vcc
	v_add_u32_e32 v228, 66, v227
	v_cmp_gt_u32_e32 vcc, v228, v3
	s_nop 1
	v_cndmask_b32_e64 v78, v78, 0, vcc
	v_add_u32_e32 v228, 67, v227
	v_cmp_gt_u32_e32 vcc, v228, v3
	s_nop 1
	v_cndmask_b32_e64 v79, v79, 0, vcc
	v_add_u32_e32 v228, 68, v227
	v_cmp_gt_u32_e32 vcc, v228, v3
	s_nop 1
	v_cndmask_b32_e64 v80, v80, 0, vcc
	v_add_u32_e32 v228, 69, v227
	v_cmp_gt_u32_e32 vcc, v228, v3
	s_nop 1
	v_cndmask_b32_e64 v81, v81, 0, vcc
	v_add_u32_e32 v228, 70, v227
	v_cmp_gt_u32_e32 vcc, v228, v3
	s_nop 1
	v_cndmask_b32_e64 v82, v82, 0, vcc
	v_add_u32_e32 v228, 71, v227
	v_cmp_gt_u32_e32 vcc, v228, v3
	s_nop 1
	v_cndmask_b32_e64 v83, v83, 0, vcc
	v_add_u32_e32 v228, 96, v227
	v_cmp_gt_u32_e32 vcc, v228, v3
	s_nop 1
	v_cndmask_b32_e64 v84, v84, 0, vcc
	v_add_u32_e32 v228, 97, v227
	v_cmp_gt_u32_e32 vcc, v228, v3
	s_nop 1
	v_cndmask_b32_e64 v85, v85, 0, vcc
	v_add_u32_e32 v228, 98, v227
	v_cmp_gt_u32_e32 vcc, v228, v3
	s_nop 1
	v_cndmask_b32_e64 v86, v86, 0, vcc
	v_add_u32_e32 v228, 99, v227
	v_cmp_gt_u32_e32 vcc, v228, v3
	s_nop 1
	v_cndmask_b32_e64 v87, v87, 0, vcc
	v_add_u32_e32 v228, 100, v227
	v_cmp_gt_u32_e32 vcc, v228, v3
	s_nop 1
	v_cndmask_b32_e64 v88, v88, 0, vcc
	v_add_u32_e32 v228, 101, v227
	v_cmp_gt_u32_e32 vcc, v228, v3
	s_nop 1
	v_cndmask_b32_e64 v89, v89, 0, vcc
	v_add_u32_e32 v228, 102, v227
	v_cmp_gt_u32_e32 vcc, v228, v3
	s_nop 1
	v_cndmask_b32_e64 v90, v90, 0, vcc
	v_add_u32_e32 v228, 103, v227
	v_cmp_gt_u32_e32 vcc, v228, v3
	s_nop 1
	v_cndmask_b32_e64 v91, v91, 0, vcc
	v_cvt_pk_bf16_f32 v12, v60, v61
	v_cvt_pk_bf16_f32 v13, v62, v63
	v_cvt_pk_bf16_f32 v14, v64, v65
	v_cvt_pk_bf16_f32 v15, v66, v67
	v_cvt_pk_bf16_f32 v16, v68, v69
	v_cvt_pk_bf16_f32 v17, v70, v71
	v_cvt_pk_bf16_f32 v18, v72, v73
	v_cvt_pk_bf16_f32 v19, v74, v75
	v_cvt_pk_bf16_f32 v20, v76, v77
	v_cvt_pk_bf16_f32 v21, v78, v79
	v_cvt_pk_bf16_f32 v22, v80, v81
	v_cvt_pk_bf16_f32 v23, v82, v83
	v_cvt_pk_bf16_f32 v24, v84, v85
	v_cvt_pk_bf16_f32 v25, v86, v87
	v_cvt_pk_bf16_f32 v26, v88, v89
	v_cvt_pk_bf16_f32 v27, v90, v91
.Lgm_loop:
	v_fmamk_f32 v36, v36, 0x3a800000, v11
	v_fmamk_f32 v37, v37, 0x3a800000, v11
	v_fmamk_f32 v38, v38, 0x3a800000, v11
	v_fmamk_f32 v39, v39, 0x3a800000, v11
	v_rsq_f32_e32 v36, v36
	v_rsq_f32_e32 v37, v37
	v_rsq_f32_e32 v38, v38
	v_rsq_f32_e32 v39, v39
	s_nop 0
	v_lshlrev_b32_e32 v230, 16, v92
	v_and_b32_e32 v231, 0xffff0000, v92
	v_mul_f32_e32 v230, v230, v36
	v_mul_f32_e32 v231, v231, v36
	v_mul_f32_e32 v230, v230, v28
	v_mul_f32_e32 v231, v231, v29
	v_cvt_pk_bf16_f32 v230, v230, v231
	ds_write_b16 v6, v230
	ds_write_b16_d16_hi v6, v230 offset:272
	v_lshlrev_b32_e32 v232, 16, v93
	v_and_b32_e32 v233, 0xffff0000, v93
	v_mul_f32_e32 v232, v232, v36
	v_mul_f32_e32 v233, v233, v36
	v_mul_f32_e32 v232, v232, v30
	v_mul_f32_e32 v233, v233, v31
	v_cvt_pk_bf16_f32 v232, v232, v233
	ds_write_b16 v6, v232 offset:544
	ds_write_b16_d16_hi v6, v232 offset:816
	v_lshlrev_b32_e32 v230, 16, v94
	v_and_b32_e32 v231, 0xffff0000, v94
	v_mul_f32_e32 v230, v230, v36
	v_mul_f32_e32 v231, v231, v36
	v_mul_f32_e32 v230, v230, v32
	v_mul_f32_e32 v231, v231, v33
	v_cvt_pk_bf16_f32 v230, v230, v231
	ds_write_b16 v6, v230 offset:1088
	ds_write_b16_d16_hi v6, v230 offset:1360
	v_lshlrev_b32_e32 v232, 16, v95
	v_and_b32_e32 v233, 0xffff0000, v95
	v_mul_f32_e32 v232, v232, v36
	v_mul_f32_e32 v233, v233, v36
	v_mul_f32_e32 v232, v232, v34
	v_mul_f32_e32 v233, v233, v35
	v_cvt_pk_bf16_f32 v232, v232, v233
	ds_write_b16 v6, v232 offset:1632
	ds_write_b16_d16_hi v6, v232 offset:1904
	v_lshlrev_b32_e32 v230, 16, v96
	v_and_b32_e32 v231, 0xffff0000, v96
	v_mul_f32_e32 v230, v230, v37
	v_mul_f32_e32 v231, v231, v37
	v_mul_f32_e32 v230, v230, v28
	v_mul_f32_e32 v231, v231, v29
	v_cvt_pk_bf16_f32 v230, v230, v231
	ds_write_b16 v239, v230
	ds_write_b16_d16_hi v239, v230 offset:272
	v_lshlrev_b32_e32 v232, 16, v97
	v_and_b32_e32 v233, 0xffff0000, v97
	v_mul_f32_e32 v232, v232, v37
	v_mul_f32_e32 v233, v233, v37
	v_mul_f32_e32 v232, v232, v30
	v_mul_f32_e32 v233, v233, v31
	v_cvt_pk_bf16_f32 v232, v232, v233
	ds_write_b16 v239, v232 offset:544
	ds_write_b16_d16_hi v239, v232 offset:816
	v_lshlrev_b32_e32 v230, 16, v98
	v_and_b32_e32 v231, 0xffff0000, v98
	v_mul_f32_e32 v230, v230, v37
	v_mul_f32_e32 v231, v231, v37
	v_mul_f32_e32 v230, v230, v32
	v_mul_f32_e32 v231, v231, v33
	v_cvt_pk_bf16_f32 v230, v230, v231
	ds_write_b16 v239, v230 offset:1088
	ds_write_b16_d16_hi v239, v230 offset:1360
	v_lshlrev_b32_e32 v232, 16, v99
	v_and_b32_e32 v233, 0xffff0000, v99
	v_mul_f32_e32 v232, v232, v37
	v_mul_f32_e32 v233, v233, v37
	v_mul_f32_e32 v232, v232, v34
	v_mul_f32_e32 v233, v233, v35
	v_cvt_pk_bf16_f32 v232, v232, v233
	ds_write_b16 v239, v232 offset:1632
	ds_write_b16_d16_hi v239, v232 offset:1904
	v_lshlrev_b32_e32 v230, 16, v100
	v_and_b32_e32 v231, 0xffff0000, v100
	v_mul_f32_e32 v230, v230, v38
	v_mul_f32_e32 v231, v231, v38
	v_mul_f32_e32 v230, v230, v28
	v_mul_f32_e32 v231, v231, v29
	v_cvt_pk_bf16_f32 v230, v230, v231
	ds_write_b16 v240, v230
	ds_write_b16_d16_hi v240, v230 offset:272
	v_lshlrev_b32_e32 v232, 16, v101
	v_and_b32_e32 v233, 0xffff0000, v101
	v_mul_f32_e32 v232, v232, v38
	v_mul_f32_e32 v233, v233, v38
	v_mul_f32_e32 v232, v232, v30
	v_mul_f32_e32 v233, v233, v31
	v_cvt_pk_bf16_f32 v232, v232, v233
	ds_write_b16 v240, v232 offset:544
	ds_write_b16_d16_hi v240, v232 offset:816
	v_lshlrev_b32_e32 v230, 16, v102
	v_and_b32_e32 v231, 0xffff0000, v102
	v_mul_f32_e32 v230, v230, v38
	v_mul_f32_e32 v231, v231, v38
	v_mul_f32_e32 v230, v230, v32
	v_mul_f32_e32 v231, v231, v33
	v_cvt_pk_bf16_f32 v230, v230, v231
	ds_write_b16 v240, v230 offset:1088
	ds_write_b16_d16_hi v240, v230 offset:1360
	v_lshlrev_b32_e32 v232, 16, v103
	v_and_b32_e32 v233, 0xffff0000, v103
	v_mul_f32_e32 v232, v232, v38
	v_mul_f32_e32 v233, v233, v38
	v_mul_f32_e32 v232, v232, v34
	v_mul_f32_e32 v233, v233, v35
	v_cvt_pk_bf16_f32 v232, v232, v233
	ds_write_b16 v240, v232 offset:1632
	ds_write_b16_d16_hi v240, v232 offset:1904
	v_lshlrev_b32_e32 v230, 16, v104
	v_and_b32_e32 v231, 0xffff0000, v104
	v_mul_f32_e32 v230, v230, v39
	v_mul_f32_e32 v231, v231, v39
	v_mul_f32_e32 v230, v230, v28
	v_mul_f32_e32 v231, v231, v29
	v_cvt_pk_bf16_f32 v230, v230, v231
	ds_write_b16 v241, v230
	ds_write_b16_d16_hi v241, v230 offset:272
	v_lshlrev_b32_e32 v232, 16, v105
	v_and_b32_e32 v233, 0xffff0000, v105
	v_mul_f32_e32 v232, v232, v39
	v_mul_f32_e32 v233, v233, v39
	v_mul_f32_e32 v232, v232, v30
	v_mul_f32_e32 v233, v233, v31
	v_cvt_pk_bf16_f32 v232, v232, v233
	ds_write_b16 v241, v232 offset:544
	ds_write_b16_d16_hi v241, v232 offset:816
	v_lshlrev_b32_e32 v230, 16, v106
	v_and_b32_e32 v231, 0xffff0000, v106
	v_mul_f32_e32 v230, v230, v39
	v_mul_f32_e32 v231, v231, v39
	v_mul_f32_e32 v230, v230, v32
	v_mul_f32_e32 v231, v231, v33
	v_cvt_pk_bf16_f32 v230, v230, v231
	ds_write_b16 v241, v230 offset:1088
	ds_write_b16_d16_hi v241, v230 offset:1360
	v_lshlrev_b32_e32 v232, 16, v107
	v_and_b32_e32 v233, 0xffff0000, v107
	v_mul_f32_e32 v232, v232, v39
	v_mul_f32_e32 v233, v233, v39
	v_mul_f32_e32 v232, v232, v34
	v_mul_f32_e32 v233, v233, v35
	v_cvt_pk_bf16_f32 v232, v232, v233
	ds_write_b16 v241, v232 offset:1632
	ds_write_b16_d16_hi v241, v232 offset:1904
	s_add_i32 s27, s8, s96
	s_cmpk_lt_i32 s27, 0x400
	s_cselect_b32 s29, s27, s8
	s_lshr_b32 s9, s29, 3
	s_mul_i32 s27, s9, 0x150000
	s_add_u32 s38, s20, s27
	s_addc_u32 s39, s21, 0
	s_add_u32 s38, s38, 0x1200
	s_addc_u32 s39, s39, 0
	s_add_u32 s34, s38, 0x800
	s_addc_u32 s35, s39, 0
	s_add_u32 s40, s38, 0x1000
	s_addc_u32 s41, s39, 0
	s_lshl_b32 s27, s9, 9
	s_add_u32 s36, s24, s27
	s_addc_u32 s37, s25, 0
	global_load_dwordx4 v[112:115], v4, s[34:35]
	global_load_dwordx4 v[116:119], v236, s[34:35]
	global_load_dwordx4 v[120:123], v237, s[34:35]
	global_load_dwordx4 v[124:127], v238, s[34:35]
	global_load_dword v40, v5, s[36:37]
	global_load_dword v41, v5, s[36:37] offset:128
	global_load_dword v42, v5, s[36:37] offset:256
	global_load_dword v43, v5, s[36:37] offset:384
	global_load_dwordx4 v[160:163], v7, s[38:39]
	global_load_dwordx4 v[164:167], v7, s[38:39] offset:64
	global_load_dwordx4 v[168:171], v7, s[38:39] offset:128
	global_load_dwordx4 v[172:175], v7, s[38:39] offset:192
	global_load_dwordx4 v[176:179], v7, s[40:41]
	global_load_dwordx4 v[180:183], v7, s[40:41] offset:64
	global_load_dwordx4 v[184:187], v7, s[40:41] offset:128
	global_load_dwordx4 v[188:191], v7, s[40:41] offset:192
	s_waitcnt lgkmcnt(0)
	s_barrier
	ds_read_b128 v[60:63], v9 offset:0
	ds_read_b128 v[64:67], v9 offset:1088
	ds_read_b128 v[68:71], v9 offset:8768
	ds_read_b128 v[72:75], v9 offset:9856
	ds_read_b128 v[76:79], v9 offset:17536
	ds_read_b128 v[80:83], v9 offset:18624
	ds_read_b128 v[84:87], v9 offset:26304
	ds_read_b128 v[88:91], v9 offset:27392
	s_waitcnt lgkmcnt(7)
	v_mfma_f32_16x16x32_bf16 v[192:195], v[60:63], v[12:15], 0
	s_waitcnt lgkmcnt(6)
	v_mfma_f32_16x16x32_bf16 v[196:199], v[64:67], v[12:15], 0
	s_waitcnt lgkmcnt(5)
	v_mfma_f32_16x16x32_bf16 v[200:203], v[68:71], v[12:15], 0
	s_waitcnt lgkmcnt(4)
	v_mfma_f32_16x16x32_bf16 v[204:207], v[72:75], v[12:15], 0
	s_waitcnt lgkmcnt(3)
	v_mfma_f32_16x16x32_bf16 v[208:211], v[76:79], v[12:15], 0
	s_waitcnt lgkmcnt(2)
	v_mfma_f32_16x16x32_bf16 v[212:215], v[80:83], v[12:15], 0
	s_waitcnt lgkmcnt(1)
	v_mfma_f32_16x16x32_bf16 v[216:219], v[84:87], v[12:15], 0
	s_waitcnt lgkmcnt(0)
	v_mfma_f32_16x16x32_bf16 v[220:223], v[88:91], v[12:15], 0
	s_cmp_lt_u32 s28, 1
	s_cbranch_scc1 .Lgm_mdone
	ds_read_b128 v[60:63], v9 offset:64
	ds_read_b128 v[64:67], v9 offset:1152
	ds_read_b128 v[68:71], v9 offset:8704
	ds_read_b128 v[72:75], v9 offset:9792
	ds_read_b128 v[76:79], v9 offset:17600
	ds_read_b128 v[80:83], v9 offset:18688
	ds_read_b128 v[84:87], v9 offset:26240
	ds_read_b128 v[88:91], v9 offset:27328
	s_waitcnt lgkmcnt(7)
	v_mfma_f32_16x16x32_bf16 v[192:195], v[60:63], v[16:19], v[192:195]
	s_waitcnt lgkmcnt(6)
	v_mfma_f32_16x16x32_bf16 v[196:199], v[64:67], v[16:19], v[196:199]
	s_waitcnt lgkmcnt(5)
	v_mfma_f32_16x16x32_bf16 v[200:203], v[68:71], v[16:19], v[200:203]
	s_waitcnt lgkmcnt(4)
	v_mfma_f32_16x16x32_bf16 v[204:207], v[72:75], v[16:19], v[204:207]
	s_waitcnt lgkmcnt(3)
	v_mfma_f32_16x16x32_bf16 v[208:211], v[76:79], v[16:19], v[208:211]
	s_waitcnt lgkmcnt(2)
	v_mfma_f32_16x16x32_bf16 v[212:215], v[80:83], v[16:19], v[212:215]
	s_waitcnt lgkmcnt(1)
	v_mfma_f32_16x16x32_bf16 v[216:219], v[84:87], v[16:19], v[216:219]
	s_waitcnt lgkmcnt(0)
	v_mfma_f32_16x16x32_bf16 v[220:223], v[88:91], v[16:19], v[220:223]
	s_cmp_lt_u32 s28, 2
	s_cbranch_scc1 .Lgm_mdone
	ds_read_b128 v[60:63], v9 offset:128
	ds_read_b128 v[64:67], v9 offset:1216
	ds_read_b128 v[68:71], v9 offset:8896
	ds_read_b128 v[72:75], v9 offset:9984
	ds_read_b128 v[76:79], v9 offset:17408
	ds_read_b128 v[80:83], v9 offset:18496
	ds_read_b128 v[84:87], v9 offset:26176
	ds_read_b128 v[88:91], v9 offset:27264
	s_waitcnt lgkmcnt(7)
	v_mfma_f32_16x16x32_bf16 v[192:195], v[60:63], v[20:23], v[192:195]
	s_waitcnt lgkmcnt(6)
	v_mfma_f32_16x16x32_bf16 v[196:199], v[64:67], v[20:23], v[196:199]
	s_waitcnt lgkmcnt(5)
	v_mfma_f32_16x16x32_bf16 v[200:203], v[68:71], v[20:23], v[200:203]
	s_waitcnt lgkmcnt(4)
	v_mfma_f32_16x16x32_bf16 v[204:207], v[72:75], v[20:23], v[204:207]
	s_waitcnt lgkmcnt(3)
	v_mfma_f32_16x16x32_bf16 v[208:211], v[76:79], v[20:23], v[208:211]
	s_waitcnt lgkmcnt(2)
	v_mfma_f32_16x16x32_bf16 v[212:215], v[80:83], v[20:23], v[212:215]
	s_waitcnt lgkmcnt(1)
	v_mfma_f32_16x16x32_bf16 v[216:219], v[84:87], v[20:23], v[216:219]
	s_waitcnt lgkmcnt(0)
	v_mfma_f32_16x16x32_bf16 v[220:223], v[88:91], v[20:23], v[220:223]
	s_cmp_lt_u32 s28, 3
	s_cbranch_scc1 .Lgm_mdone
	ds_read_b128 v[60:63], v9 offset:192
	ds_read_b128 v[64:67], v9 offset:1280
	ds_read_b128 v[68:71], v9 offset:8832
	ds_read_b128 v[72:75], v9 offset:9920
	ds_read_b128 v[76:79], v9 offset:17472
	ds_read_b128 v[80:83], v9 offset:18560
	ds_read_b128 v[84:87], v9 offset:26112
	ds_read_b128 v[88:91], v9 offset:27200
	s_waitcnt lgkmcnt(7)
	v_mfma_f32_16x16x32_bf16 v[192:195], v[60:63], v[24:27], v[192:195]
	s_waitcnt lgkmcnt(6)
	v_mfma_f32_16x16x32_bf16 v[196:199], v[64:67], v[24:27], v[196:199]
	s_waitcnt lgkmcnt(5)
	v_mfma_f32_16x16x32_bf16 v[200:203], v[68:71], v[24:27], v[200:203]
	s_waitcnt lgkmcnt(4)
	v_mfma_f32_16x16x32_bf16 v[204:207], v[72:75], v[24:27], v[204:207]
	s_waitcnt lgkmcnt(3)
	v_mfma_f32_16x16x32_bf16 v[208:211], v[76:79], v[24:27], v[208:211]
	s_waitcnt lgkmcnt(2)
	v_mfma_f32_16x16x32_bf16 v[212:215], v[80:83], v[24:27], v[212:215]
	s_waitcnt lgkmcnt(1)
	v_mfma_f32_16x16x32_bf16 v[216:219], v[84:87], v[24:27], v[216:219]
	s_waitcnt lgkmcnt(0)
	v_mfma_f32_16x16x32_bf16 v[220:223], v[88:91], v[24:27], v[220:223]
.Lgm_mdone:
	s_waitcnt lgkmcnt(0)
	s_barrier
	s_nop 7
	v_lshlrev_b32_e32 v224, 16, v128
	v_and_b32_e32 v225, 0xffff0000, v128
	v_lshlrev_b32_e32 v226, 16, v129
	v_and_b32_e32 v227, 0xffff0000, v129
	v_lshlrev_b32_e32 v228, 16, v144
	v_and_b32_e32 v229, 0xffff0000, v144
	v_lshlrev_b32_e32 v230, 16, v145
	v_and_b32_e32 v231, 0xffff0000, v145
	v_add_f32_e32 v192, v192, v10
	v_add_f32_e32 v193, v193, v10
	v_add_f32_e32 v194, v194, v10
	v_add_f32_e32 v195, v195, v10
	v_mul_f32_e32 v192, v224, v192
	v_mul_f32_e32 v193, v225, v193
	v_mul_f32_e32 v194, v226, v194
	v_mul_f32_e32 v195, v227, v195
	v_mul_f32_e32 v192, v192, v228
	v_mul_f32_e32 v193, v193, v229
	v_mul_f32_e32 v194, v194, v230
	v_mul_f32_e32 v195, v195, v231
	v_lshlrev_b32_e32 v224, 16, v130
	v_and_b32_e32 v225, 0xffff0000, v130
	v_lshlrev_b32_e32 v226, 16, v131
	v_and_b32_e32 v227, 0xffff0000, v131
	v_lshlrev_b32_e32 v228, 16, v146
	v_and_b32_e32 v229, 0xffff0000, v146
	v_lshlrev_b32_e32 v230, 16, v147
	v_and_b32_e32 v231, 0xffff0000, v147
	v_add_f32_e32 v196, v196, v10
	v_add_f32_e32 v197, v197, v10
	v_add_f32_e32 v198, v198, v10
	v_add_f32_e32 v199, v199, v10
	v_mul_f32_e32 v196, v224, v196
	v_mul_f32_e32 v197, v225, v197
	v_mul_f32_e32 v198, v226, v198
	v_mul_f32_e32 v199, v227, v199
	v_mul_f32_e32 v196, v196, v228
	v_mul_f32_e32 v197, v197, v229
	v_mul_f32_e32 v198, v198, v230
	v_mul_f32_e32 v199, v199, v231
	v_cvt_pk_bf16_f32 v192, v192, v193
	v_cvt_pk_bf16_f32 v193, v194, v195
	v_cvt_pk_bf16_f32 v194, v196, v197
	v_cvt_pk_bf16_f32 v195, v198, v199
	global_store_dwordx4 v8, v[192:195], s[18:19]
	v_lshlrev_b32_e32 v224, 16, v132
	v_and_b32_e32 v225, 0xffff0000, v132
	v_lshlrev_b32_e32 v226, 16, v133
	v_and_b32_e32 v227, 0xffff0000, v133
	v_lshlrev_b32_e32 v228, 16, v148
	v_and_b32_e32 v229, 0xffff0000, v148
	v_lshlrev_b32_e32 v230, 16, v149
	v_and_b32_e32 v231, 0xffff0000, v149
	v_add_f32_e32 v200, v200, v10
	v_add_f32_e32 v201, v201, v10
	v_add_f32_e32 v202, v202, v10
	v_add_f32_e32 v203, v203, v10
	v_mul_f32_e32 v200, v224, v200
	v_mul_f32_e32 v201, v225, v201
	v_mul_f32_e32 v202, v226, v202
	v_mul_f32_e32 v203, v227, v203
	v_mul_f32_e32 v200, v200, v228
	v_mul_f32_e32 v201, v201, v229
	v_mul_f32_e32 v202, v202, v230
	v_mul_f32_e32 v203, v203, v231
	v_lshlrev_b32_e32 v224, 16, v134
	v_and_b32_e32 v225, 0xffff0000, v134
	v_lshlrev_b32_e32 v226, 16, v135
	v_and_b32_e32 v227, 0xffff0000, v135
	v_lshlrev_b32_e32 v228, 16, v150
	v_and_b32_e32 v229, 0xffff0000, v150
	v_lshlrev_b32_e32 v230, 16, v151
	v_and_b32_e32 v231, 0xffff0000, v151
	v_add_f32_e32 v204, v204, v10
	v_add_f32_e32 v205, v205, v10
	v_add_f32_e32 v206, v206, v10
	v_add_f32_e32 v207, v207, v10
	v_mul_f32_e32 v204, v224, v204
	v_mul_f32_e32 v205, v225, v205
	v_mul_f32_e32 v206, v226, v206
	v_mul_f32_e32 v207, v227, v207
	v_mul_f32_e32 v204, v204, v228
	v_mul_f32_e32 v205, v205, v229
	v_mul_f32_e32 v206, v206, v230
	v_mul_f32_e32 v207, v207, v231
	v_cvt_pk_bf16_f32 v200, v200, v201
	v_cvt_pk_bf16_f32 v201, v202, v203
	v_cvt_pk_bf16_f32 v202, v204, v205
	v_cvt_pk_bf16_f32 v203, v206, v207
	global_store_dwordx4 v8, v[200:203], s[18:19] offset:64
	v_lshlrev_b32_e32 v224, 16, v136
	v_and_b32_e32 v225, 0xffff0000, v136
	v_lshlrev_b32_e32 v226, 16, v137
	v_and_b32_e32 v227, 0xffff0000, v137
	v_lshlrev_b32_e32 v228, 16, v152
	v_and_b32_e32 v229, 0xffff0000, v152
	v_lshlrev_b32_e32 v230, 16, v153
	v_and_b32_e32 v231, 0xffff0000, v153
	v_add_f32_e32 v208, v208, v10
	v_add_f32_e32 v209, v209, v10
	v_add_f32_e32 v210, v210, v10
	v_add_f32_e32 v211, v211, v10
	v_mul_f32_e32 v208, v224, v208
	v_mul_f32_e32 v209, v225, v209
	v_mul_f32_e32 v210, v226, v210
	v_mul_f32_e32 v211, v227, v211
	v_mul_f32_e32 v208, v208, v228
	v_mul_f32_e32 v209, v209, v229
	v_mul_f32_e32 v210, v210, v230
	v_mul_f32_e32 v211, v211, v231
	v_lshlrev_b32_e32 v224, 16, v138
	v_and_b32_e32 v225, 0xffff0000, v138
	v_lshlrev_b32_e32 v226, 16, v139
	v_and_b32_e32 v227, 0xffff0000, v139
	v_lshlrev_b32_e32 v228, 16, v154
	v_and_b32_e32 v229, 0xffff0000, v154
	v_lshlrev_b32_e32 v230, 16, v155
	v_and_b32_e32 v231, 0xffff0000, v155
	v_add_f32_e32 v212, v212, v10
	v_add_f32_e32 v213, v213, v10
	v_add_f32_e32 v214, v214, v10
	v_add_f32_e32 v215, v215, v10
	v_mul_f32_e32 v212, v224, v212
	v_mul_f32_e32 v213, v225, v213
	v_mul_f32_e32 v214, v226, v214
	v_mul_f32_e32 v215, v227, v215
	v_mul_f32_e32 v212, v212, v228
	v_mul_f32_e32 v213, v213, v229
	v_mul_f32_e32 v214, v214, v230
	v_mul_f32_e32 v215, v215, v231
	v_cvt_pk_bf16_f32 v208, v208, v209
	v_cvt_pk_bf16_f32 v209, v210, v211
	v_cvt_pk_bf16_f32 v210, v212, v213
	v_cvt_pk_bf16_f32 v211, v214, v215
	global_store_dwordx4 v8, v[208:211], s[18:19] offset:128
	v_lshlrev_b32_e32 v224, 16, v140
	v_and_b32_e32 v225, 0xffff0000, v140
	v_lshlrev_b32_e32 v226, 16, v141
	v_and_b32_e32 v227, 0xffff0000, v141
	v_lshlrev_b32_e32 v228, 16, v156
	v_and_b32_e32 v229, 0xffff0000, v156
	v_lshlrev_b32_e32 v230, 16, v157
	v_and_b32_e32 v231, 0xffff0000, v157
	v_add_f32_e32 v216, v216, v10
	v_add_f32_e32 v217, v217, v10
	v_add_f32_e32 v218, v218, v10
	v_add_f32_e32 v219, v219, v10
	v_mul_f32_e32 v216, v224, v216
	v_mul_f32_e32 v217, v225, v217
	v_mul_f32_e32 v218, v226, v218
	v_mul_f32_e32 v219, v227, v219
	v_mul_f32_e32 v216, v216, v228
	v_mul_f32_e32 v217, v217, v229
	v_mul_f32_e32 v218, v218, v230
	v_mul_f32_e32 v219, v219, v231
	v_lshlrev_b32_e32 v224, 16, v142
	v_and_b32_e32 v225, 0xffff0000, v142
	v_lshlrev_b32_e32 v226, 16, v143
	v_and_b32_e32 v227, 0xffff0000, v143
	v_lshlrev_b32_e32 v228, 16, v158
	v_and_b32_e32 v229, 0xffff0000, v158
	v_lshlrev_b32_e32 v230, 16, v159
	v_and_b32_e32 v231, 0xffff0000, v159
	v_add_f32_e32 v220, v220, v10
	v_add_f32_e32 v221, v221, v10
	v_add_f32_e32 v222, v222, v10
	v_add_f32_e32 v223, v223, v10
	v_mul_f32_e32 v220, v224, v220
	v_mul_f32_e32 v221, v225, v221
	v_mul_f32_e32 v222, v226, v222
	v_mul_f32_e32 v223, v227, v223
	v_mul_f32_e32 v220, v220, v228
	v_mul_f32_e32 v221, v221, v229
	v_mul_f32_e32 v222, v222, v230
	v_mul_f32_e32 v223, v223, v231
	v_cvt_pk_bf16_f32 v216, v216, v217
	v_cvt_pk_bf16_f32 v217, v218, v219
	v_cvt_pk_bf16_f32 v218, v220, v221
	v_cvt_pk_bf16_f32 v219, v222, v223
	global_store_dwordx4 v8, v[216:219], s[18:19] offset:192
	s_waitcnt vmcnt(4)
	v_mov_b32_e32 v92, v112
	v_mov_b32_e32 v93, v113
	v_mov_b32_e32 v94, v114
	v_mov_b32_e32 v95, v115
	v_mov_b32_e32 v96, v116
	v_mov_b32_e32 v97, v117
	v_mov_b32_e32 v98, v118
	v_mov_b32_e32 v99, v119
	v_mov_b32_e32 v100, v120
	v_mov_b32_e32 v101, v121
	v_mov_b32_e32 v102, v122
	v_mov_b32_e32 v103, v123
	v_mov_b32_e32 v104, v124
	v_mov_b32_e32 v105, v125
	v_mov_b32_e32 v106, v126
	v_mov_b32_e32 v107, v127
	v_mov_b32_e32 v36, v40
	v_mov_b32_e32 v37, v41
	v_mov_b32_e32 v38, v42
	v_mov_b32_e32 v39, v43
	v_mov_b32_e32 v128, v160
	v_mov_b32_e32 v129, v161
	v_mov_b32_e32 v130, v162
	v_mov_b32_e32 v131, v163
	v_mov_b32_e32 v132, v164
	v_mov_b32_e32 v133, v165
	v_mov_b32_e32 v134, v166
	v_mov_b32_e32 v135, v167
	v_mov_b32_e32 v136, v168
	v_mov_b32_e32 v137, v169
	v_mov_b32_e32 v138, v170
	v_mov_b32_e32 v139, v171
	v_mov_b32_e32 v140, v172
	v_mov_b32_e32 v141, v173
	v_mov_b32_e32 v142, v174
	v_mov_b32_e32 v143, v175
	v_mov_b32_e32 v144, v176
	v_mov_b32_e32 v145, v177
	v_mov_b32_e32 v146, v178
	v_mov_b32_e32 v147, v179
	v_mov_b32_e32 v148, v180
	v_mov_b32_e32 v149, v181
	v_mov_b32_e32 v150, v182
	v_mov_b32_e32 v151, v183
	v_mov_b32_e32 v152, v184
	v_mov_b32_e32 v153, v185
	v_mov_b32_e32 v154, v186
	v_mov_b32_e32 v155, v187
	v_mov_b32_e32 v156, v188
	v_mov_b32_e32 v157, v189
	v_mov_b32_e32 v158, v190
	v_mov_b32_e32 v159, v191
	s_lshr_b32 s9, s29, 3
	s_lshl_b32 s27, s9, 19
	s_add_u32 s18, s22, s27
	s_addc_u32 s19, s23, 0
	s_add_i32 s8, s8, s96
	s_cmpk_lt_i32 s8, 0x400
	s_cbranch_scc1 .Lgm_loop
